# short-conv loop rewritten: weights loaded once, the 7 row loads of an iteration issued together (was 4 serialized load-wait groups)
# speedup vs baseline: 1.0132x; 1.0132x over previous
.LBB0_456:
	s_load_dword s0, s[22:23], 0x10
	s_waitcnt lgkmcnt(0)
	s_lshr_b32 s0, s0, 16
	s_cmp_lg_u32 s0, 0
	s_cselect_b64 s[0:1], -1, 0
	s_cmp_lg_u64 s[0:1], 0
	s_addc_u32 s2, s2, 0
	s_cmpk_gt_u32 s2, 0xff
	s_cselect_b32 s4, 0x80, 0
	s_cmp_ge_i32 s90, s4
	s_cbranch_scc0 .LBB0_467
	s_sub_i32 s36, s90, s4
	s_waitcnt vmcnt(7)
	v_mov_b32_e32 v2, v169
	s_lshl_b64 s[0:1], s[36:37], 8
	s_nop 0
	v_ashrrev_i32_e32 v3, 31, v2
	s_waitcnt vmcnt(5)
	v_lshl_add_u64 v[10:11], s[0:1], 0, v[2:3]
	s_mov_b64 s[0:1], 0x200000
	v_cmp_gt_u64_e32 vcc, s[0:1], v[10:11]
	s_and_saveexec_b64 s[0:1], vcc
	s_cbranch_execz .LBB0_466
	s_add_u32 s5, s72, s40
	s_addc_u32 s8, s73, s41
	s_add_u32 s28, s5, 0xa991000
	s_addc_u32 s29, s8, 0
	s_add_u32 s34, s5, 0x8991000
	s_addc_u32 s35, s8, 0
	v_readlane_b32 s8, v255, 36
	v_readlane_b32 s40, v253, 2
	s_mul_hi_i32 s5, s8, 0x1800
	s_mulk_i32 s8, 0x1800
	v_readlane_b32 s44, v253, 6
	v_readlane_b32 s9, v255, 37
	v_readlane_b32 s45, v253, 7
	s_add_u32 s38, s44, s8
	v_readlane_b32 s41, v253, 3
	v_readlane_b32 s42, v253, 4
	v_readlane_b32 s43, v253, 5
	s_addc_u32 s39, s45, s5
	s_sub_i32 s4, s2, s4
	s_mov_b32 s5, s37
	s_lshl_b64 s[8:9], s[36:37], 11
	s_lshl_b64 s[40:41], s[4:5], 8
	v_lshl_add_u64 v[12:13], v[2:3], 3, s[8:9]
	s_lshl_b64 s[42:43], s[4:5], 11
	s_mov_b64 s[44:45], 0
	v_readlane_b32 s46, v253, 8
	v_readlane_b32 s47, v253, 9
	v_readlane_b32 s48, v253, 10
	v_readlane_b32 s49, v253, 11
	v_readlane_b32 s50, v253, 12
	v_readlane_b32 s51, v253, 13
	v_readlane_b32 s52, v253, 14
	v_readlane_b32 s53, v253, 15
	v_readlane_b32 s54, v253, 16
	v_readlane_b32 s55, v253, 17
	v_and_b32_e32 v21, 0x1f8, v12
	v_lshlrev_b32_e32 v0, 2, v21
	v_lshl_add_u64 v[18:19], s[38:39], 0, v[0:1]
	global_load_dwordx4 v[64:67], v[18:19], off
	global_load_dwordx4 v[68:71], v[18:19], off offset:16
	global_load_dwordx4 v[72:75], v[18:19], off offset:2048
	global_load_dwordx4 v[76:79], v[18:19], off offset:2064
	s_mov_b64 s[4:5], 0x1000
	v_lshl_add_u64 v[18:19], v[18:19], 0, s[4:5]
	global_load_dwordx4 v[80:83], v[18:19], off
	global_load_dwordx4 v[84:87], v[18:19], off offset:16
	v_mov_b32_e32 v62, 0x1800
	v_mov_b32_e32 v63, 0xc00
	s_waitcnt vmcnt(0)
	s_branch .LBB0_460
.LBB0_460:
	v_alignbit_b32 v16, v11, v10, 6
	v_and_b32_e32 v21, 0x1f8, v12
	v_and_b32_e32 v22, 0x1fff, v16
	v_lshlrev_b32_e32 v14, 1, v21
	v_mul_u32_u24_e32 v17, 0xc00, v16
	v_cmp_lt_u32_e64 s[98:99], 1, v22
	v_cmp_ne_u32_e64 s[100:101], 0, v22
	v_add_u32_e32 v17, v17, v14
	v_lshlrev_b32_e32 v23, 10, v16
	v_cndmask_b32_e64 v20, 0, v62, s[98:99]
	v_cndmask_b32_e64 v24, 0, v63, s[100:101]
	v_sub_u32_e32 v20, v17, v20
	v_sub_u32_e32 v24, v17, v24
	global_load_dwordx4 v[26:29], v20, s[28:29] offset:1024
	global_load_dwordx4 v[30:33], v20, s[28:29] offset:2048
	global_load_dwordx4 v[34:37], v24, s[28:29] offset:1024
	global_load_dwordx4 v[38:41], v24, s[28:29] offset:2048
	global_load_dwordx4 v[42:45], v17, s[28:29] offset:1024
	global_load_dwordx4 v[46:49], v17, s[28:29] offset:2048
	global_load_dwordx4 v[50:53], v17, s[28:29]
	v_add_u32_e32 v23, v23, v14
	v_mov_b32_e32 v2, v1
	v_mov_b32_e32 v3, v1
	v_mov_b32_e32 v4, v1
	v_mov_b32_e32 v5, v1
	v_mov_b32_e32 v6, v1
	v_mov_b32_e32 v7, v1
	v_mov_b32_e32 v8, v1
	v_mov_b32_e32 v9, v1
	s_waitcnt vmcnt(5)
	s_and_saveexec_b64 s[4:5], s[98:99]
	v_lshlrev_b32_e32 v54, 16, v26
	v_and_b32_e32 v55, 0xffff0000, v26
	v_lshlrev_b32_e32 v56, 16, v27
	v_and_b32_e32 v57, 0xffff0000, v27
	v_lshlrev_b32_e32 v58, 16, v28
	v_and_b32_e32 v59, 0xffff0000, v28
	v_lshlrev_b32_e32 v60, 16, v29
	v_and_b32_e32 v61, 0xffff0000, v29
	v_pk_mul_f32 v[88:89], v[64:65], v[54:55]
	v_pk_mul_f32 v[90:91], v[66:67], v[56:57]
	v_pk_mul_f32 v[92:93], v[68:69], v[58:59]
	v_pk_mul_f32 v[94:95], v[70:71], v[60:61]
	v_lshlrev_b32_e32 v54, 16, v30
	v_and_b32_e32 v55, 0xffff0000, v30
	v_lshlrev_b32_e32 v56, 16, v31
	v_and_b32_e32 v57, 0xffff0000, v31
	v_lshlrev_b32_e32 v58, 16, v32
	v_and_b32_e32 v59, 0xffff0000, v32
	v_lshlrev_b32_e32 v60, 16, v33
	v_and_b32_e32 v61, 0xffff0000, v33
	v_pk_fma_f32 v[2:3], v[88:89], v[54:55], v[2:3]
	v_pk_fma_f32 v[4:5], v[90:91], v[56:57], v[4:5]
	v_pk_fma_f32 v[6:7], v[92:93], v[58:59], v[6:7]
	v_pk_fma_f32 v[8:9], v[94:95], v[60:61], v[8:9]
	s_or_b64 exec, exec, s[4:5]
	s_waitcnt vmcnt(3)
	s_and_saveexec_b64 s[4:5], s[100:101]
	v_lshlrev_b32_e32 v54, 16, v34
	v_and_b32_e32 v55, 0xffff0000, v34
	v_lshlrev_b32_e32 v56, 16, v35
	v_and_b32_e32 v57, 0xffff0000, v35
	v_lshlrev_b32_e32 v58, 16, v36
	v_and_b32_e32 v59, 0xffff0000, v36
	v_lshlrev_b32_e32 v60, 16, v37
	v_and_b32_e32 v61, 0xffff0000, v37
	v_pk_mul_f32 v[88:89], v[72:73], v[54:55]
	v_pk_mul_f32 v[90:91], v[74:75], v[56:57]
	v_pk_mul_f32 v[92:93], v[76:77], v[58:59]
	v_pk_mul_f32 v[94:95], v[78:79], v[60:61]
	v_lshlrev_b32_e32 v54, 16, v38
	v_and_b32_e32 v55, 0xffff0000, v38
	v_lshlrev_b32_e32 v56, 16, v39
	v_and_b32_e32 v57, 0xffff0000, v39
	v_lshlrev_b32_e32 v58, 16, v40
	v_and_b32_e32 v59, 0xffff0000, v40
	v_lshlrev_b32_e32 v60, 16, v41
	v_and_b32_e32 v61, 0xffff0000, v41
	v_pk_fma_f32 v[2:3], v[88:89], v[54:55], v[2:3]
	v_pk_fma_f32 v[4:5], v[90:91], v[56:57], v[4:5]
	v_pk_fma_f32 v[6:7], v[92:93], v[58:59], v[6:7]
	v_pk_fma_f32 v[8:9], v[94:95], v[60:61], v[8:9]
	s_or_b64 exec, exec, s[4:5]
	s_waitcnt vmcnt(1)
	v_lshlrev_b32_e32 v54, 16, v42
	v_and_b32_e32 v55, 0xffff0000, v42
	v_lshlrev_b32_e32 v56, 16, v43
	v_and_b32_e32 v57, 0xffff0000, v43
	v_lshlrev_b32_e32 v58, 16, v44
	v_and_b32_e32 v59, 0xffff0000, v44
	v_lshlrev_b32_e32 v60, 16, v45
	v_and_b32_e32 v61, 0xffff0000, v45
	v_pk_mul_f32 v[88:89], v[80:81], v[54:55]
	v_pk_mul_f32 v[90:91], v[82:83], v[56:57]
	v_pk_mul_f32 v[92:93], v[84:85], v[58:59]
	v_pk_mul_f32 v[94:95], v[86:87], v[60:61]
	v_lshlrev_b32_e32 v54, 16, v46
	v_and_b32_e32 v55, 0xffff0000, v46
	v_lshlrev_b32_e32 v56, 16, v47
	v_and_b32_e32 v57, 0xffff0000, v47
	v_lshlrev_b32_e32 v58, 16, v48
	v_and_b32_e32 v59, 0xffff0000, v48
	v_lshlrev_b32_e32 v60, 16, v49
	v_and_b32_e32 v61, 0xffff0000, v49
	v_pk_fma_f32 v[2:3], v[88:89], v[54:55], v[2:3]
	v_pk_fma_f32 v[4:5], v[90:91], v[56:57], v[4:5]
	v_pk_fma_f32 v[6:7], v[92:93], v[58:59], v[6:7]
	v_pk_fma_f32 v[8:9], v[94:95], v[60:61], v[8:9]
	s_waitcnt vmcnt(0)
	v_lshlrev_b32_e32 v54, 16, v50
	v_and_b32_e32 v55, 0xffff0000, v50
	v_lshlrev_b32_e32 v56, 16, v51
	v_and_b32_e32 v57, 0xffff0000, v51
	v_lshlrev_b32_e32 v58, 16, v52
	v_and_b32_e32 v59, 0xffff0000, v52
	v_lshlrev_b32_e32 v60, 16, v53
	v_and_b32_e32 v61, 0xffff0000, v53
	v_pk_mul_f32 v[2:3], v[2:3], v[54:55]
	v_pk_mul_f32 v[4:5], v[4:5], v[56:57]
	v_pk_mul_f32 v[6:7], v[6:7], v[58:59]
	v_pk_mul_f32 v[8:9], v[8:9], v[60:61]
	v_cvt_pk_bf16_f32 v2, v2, v3
	v_cvt_pk_bf16_f32 v3, v4, v5
	v_cvt_pk_bf16_f32 v4, v6, v7
	v_cvt_pk_bf16_f32 v5, v8, v9
	global_store_dwordx4 v23, v[2:5], s[34:35]
	v_lshl_add_u64 v[10:11], v[10:11], 0, s[40:41]
	v_lshl_add_u64 v[12:13], v[12:13], 0, s[42:43]
	s_mov_b64 s[4:5], 0x1fffff
	v_cmp_lt_u64_e32 vcc, s[4:5], v[10:11]
	s_or_b64 s[44:45], vcc, s[44:45]
	s_andn2_b64 exec, exec, s[44:45]
	s_cbranch_execnz .LBB0_460
